# v28 + instruction selection: 64-bit moves for per-unit accumulator zeroing, NaN-canonicalising max pairs folded in the softmax row-max
# speedup vs baseline: 1.0029x; 1.0029x over previous
.LBB0_421:
	s_ashr_i32 s21, s20, 31
	s_lshl_b64 s[22:23], s[20:21], 15
	v_readlane_b32 s9, v245, 12
	s_add_u32 s22, s9, s22
	v_readlane_b32 s9, v245, 13
	s_addc_u32 s23, s9, s23
	s_and_b64 s[24:25], s[6:7], exec
	s_cselect_b32 s9, s23, s31
	s_cselect_b32 s21, s22, s30
	s_ashr_i32 s19, s18, 31
	s_lshl_b64 s[24:25], s[18:19], 15
	s_add_u32 s24, s4, s24
	s_addc_u32 s25, s5, s25
	s_and_b64 s[34:35], s[6:7], exec
	s_cselect_b32 s19, s25, s29
	s_cselect_b32 s50, s24, s28
	s_add_u32 s51, s28, 0x700000
	s_addc_u32 s52, s29, 0
	s_add_u32 s28, s30, 0x104000
	v_mov_b32_e32 v2, 0
	s_addc_u32 s29, s31, 0
	s_mov_b32 s53, -2
	v_mov_b32_e32 v3, v2
	v_mov_b32_e32 v4, v2
	v_mov_b32_e32 v5, v2
	v_mov_b32_e32 v6, v2
	v_mov_b32_e32 v7, v2
	v_mov_b32_e32 v8, v2
	v_mov_b32_e32 v9, v2
	v_mov_b32_e32 v18, v2
	v_mov_b32_e32 v19, v2
	v_mov_b32_e32 v20, v2
	v_mov_b32_e32 v21, v2
	v_mov_b32_e32 v22, v2
	v_mov_b32_e32 v23, v2
	v_mov_b32_e32 v24, v2
	v_mov_b32_e32 v25, v2
	s_waitcnt vmcnt(0)
	v_mov_b64_e32 v[10:11], 0
	v_mov_b64_e32 v[12:13], 0
	v_mov_b64_e32 v[14:15], 0
	v_mov_b64_e32 v[16:17], 0
	v_mov_b64_e32 v[26:27], 0
	v_mov_b64_e32 v[28:29], 0
	v_mov_b64_e32 v[30:31], 0
	v_mov_b64_e32 v[32:33], 0
	v_mov_b64_e32 v[34:35], 0
	v_mov_b64_e32 v[36:37], 0
	v_mov_b64_e32 v[38:39], 0
	v_mov_b64_e32 v[40:41], 0
	v_mov_b64_e32 v[42:43], 0
	v_mov_b64_e32 v[44:45], 0
	v_mov_b64_e32 v[46:47], 0
	v_mov_b64_e32 v[48:49], 0
	v_mov_b64_e32 v[50:51], 0
	v_mov_b64_e32 v[52:53], 0
	v_mov_b64_e32 v[54:55], 0
	v_mov_b64_e32 v[56:57], 0
	v_mov_b64_e32 v[58:59], 0
	v_mov_b64_e32 v[60:61], 0
	v_mov_b64_e32 v[62:63], 0
	v_mov_b64_e32 v[64:65], 0
	v_mov_b64_e32 v[66:67], 0
	v_mov_b64_e32 v[68:69], 0
	v_mov_b64_e32 v[70:71], 0
	v_mov_b64_e32 v[72:73], 0
	v_mov_b64_e32 v[74:75], 0
	v_mov_b64_e32 v[76:77], 0
	v_mov_b64_e32 v[78:79], 0
	v_mov_b64_e32 v[80:81], 0
	v_mov_b64_e32 v[82:83], 0
	v_mov_b64_e32 v[84:85], 0
	v_mov_b64_e32 v[86:87], 0
	v_mov_b64_e32 v[88:89], 0
	v_mov_b64_e32 v[90:91], 0
	v_mov_b64_e32 v[92:93], 0
	v_mov_b64_e32 v[94:95], 0
	v_mov_b64_e32 v[96:97], 0
	v_mov_b64_e32 v[98:99], 0
	v_mov_b64_e32 v[100:101], 0
	v_mov_b64_e32 v[102:103], 0
	v_mov_b64_e32 v[104:105], 0
	v_mov_b64_e32 v[106:107], 0
	v_mov_b64_e32 v[108:109], 0
	v_mov_b64_e32 v[110:111], 0
	v_mov_b64_e32 v[112:113], 0
	v_mov_b64_e32 v[114:115], 0
	v_mov_b64_e32 v[116:117], 0
	v_mov_b64_e32 v[118:119], 0
	v_mov_b64_e32 v[120:121], 0
	v_mov_b64_e32 v[122:123], 0
	v_mov_b64_e32 v[124:125], 0
	v_mov_b64_e32 v[126:127], 0
	v_mov_b64_e32 v[128:129], 0

.LBB0_500:
	s_ashr_i32 s21, s20, 31
	s_lshl_b64 s[22:23], s[20:21], 15
	v_readlane_b32 s24, v245, 14
	v_readlane_b32 s25, v245, 15
	s_add_u32 s22, s24, s22
	s_addc_u32 s23, s25, s23
	s_and_b64 s[24:25], s[6:7], exec
	s_cselect_b32 s5, s23, s27
	s_cselect_b32 s21, s22, s26
	s_ashr_i32 s19, s18, 31
	s_lshl_b64 s[24:25], s[18:19], 15
	v_readlane_b32 s28, v245, 8
	v_readlane_b32 s29, v245, 9
	s_add_u32 s24, s28, s24
	s_addc_u32 s25, s29, s25
	s_and_b64 s[28:29], s[6:7], exec
	s_cselect_b32 s19, s25, s11
	s_cselect_b32 s44, s24, s10
	s_add_u32 s45, s10, 0x100000
	s_addc_u32 s46, s11, 0
	s_add_u32 s10, s26, 0x104000
	v_mov_b32_e32 v2, 0
	s_addc_u32 s11, s27, 0
	s_mov_b32 s47, -2
	v_mov_b32_e32 v3, 0
	v_mov_b64_e32 v[4:5], 0
	v_mov_b64_e32 v[6:7], 0
	v_mov_b64_e32 v[8:9], 0
	v_mov_b64_e32 v[10:11], 0
	v_mov_b64_e32 v[12:13], 0
	v_mov_b64_e32 v[14:15], 0
	v_mov_b64_e32 v[16:17], 0
	v_mov_b64_e32 v[18:19], 0
	v_mov_b64_e32 v[20:21], 0
	v_mov_b64_e32 v[22:23], 0
	v_mov_b64_e32 v[24:25], 0
	v_mov_b64_e32 v[26:27], 0
	v_mov_b64_e32 v[28:29], 0
	v_mov_b64_e32 v[30:31], 0
	v_mov_b64_e32 v[32:33], 0
	v_mov_b64_e32 v[34:35], 0
	v_mov_b64_e32 v[36:37], 0
	v_mov_b64_e32 v[38:39], 0
	v_mov_b64_e32 v[40:41], 0
	v_mov_b64_e32 v[42:43], 0
	v_mov_b64_e32 v[44:45], 0
	v_mov_b64_e32 v[46:47], 0
	v_mov_b64_e32 v[48:49], 0
	v_mov_b64_e32 v[50:51], 0
	v_mov_b64_e32 v[52:53], 0
	v_mov_b64_e32 v[54:55], 0
	v_mov_b64_e32 v[56:57], 0
	v_mov_b64_e32 v[58:59], 0
	v_mov_b64_e32 v[60:61], 0
	v_mov_b64_e32 v[62:63], 0
	v_mov_b64_e32 v[64:65], 0
	v_mov_b64_e32 v[66:67], 0
	v_mov_b64_e32 v[68:69], 0
	v_mov_b64_e32 v[70:71], 0
	v_mov_b64_e32 v[72:73], 0
	v_mov_b64_e32 v[74:75], 0
	v_mov_b64_e32 v[76:77], 0
	v_mov_b64_e32 v[78:79], 0
	v_mov_b64_e32 v[80:81], 0
	v_mov_b64_e32 v[82:83], 0
	v_mov_b64_e32 v[84:85], 0
	v_mov_b64_e32 v[86:87], 0
	v_mov_b64_e32 v[88:89], 0
	v_mov_b64_e32 v[90:91], 0
	v_mov_b64_e32 v[92:93], 0
	v_mov_b64_e32 v[94:95], 0
	v_mov_b64_e32 v[96:97], 0
	v_mov_b64_e32 v[98:99], 0
	v_mov_b64_e32 v[100:101], 0
	v_mov_b64_e32 v[102:103], 0
	v_mov_b64_e32 v[104:105], 0
	v_mov_b64_e32 v[106:107], 0
	v_mov_b64_e32 v[108:109], 0
	v_mov_b64_e32 v[110:111], 0
	v_mov_b64_e32 v[112:113], 0
	v_mov_b64_e32 v[114:115], 0
	v_mov_b64_e32 v[116:117], 0
	v_mov_b64_e32 v[118:119], 0
	v_mov_b64_e32 v[120:121], 0
	v_mov_b64_e32 v[122:123], 0
	v_mov_b64_e32 v[124:125], 0
	v_mov_b64_e32 v[126:127], 0
	v_mov_b64_e32 v[128:129], 0
	s_waitcnt lgkmcnt(0)

.LBB0_800:
	s_ashr_i32 s21, s20, 31
	s_lshl_b64 s[22:23], s[20:21], 15
	v_readlane_b32 s3, v245, 12
	s_add_u32 s22, s3, s22
	v_readlane_b32 s3, v245, 13
	s_addc_u32 s23, s3, s23
	s_and_b64 s[24:25], s[10:11], exec
	s_cselect_b32 s3, s23, s27
	s_cselect_b32 s5, s22, s26
	s_ashr_i32 s19, s18, 31
	s_lshl_b64 s[24:25], s[18:19], 15
	v_readlane_b32 s28, v245, 6
	v_readlane_b32 s29, v245, 7
	s_add_u32 s24, s28, s24
	s_addc_u32 s25, s29, s25
	s_and_b64 s[28:29], s[10:11], exec
	s_cselect_b32 s19, s25, s13
	s_cselect_b32 s21, s24, s12
	s_add_u32 s45, s12, 0x300000
	s_addc_u32 s46, s13, 0
	s_add_u32 s12, s26, 0x104000
	v_mov_b32_e32 v2, 0
	s_addc_u32 s13, s27, 0
	s_mov_b32 s47, -2
	v_mov_b32_e32 v3, v2
	v_mov_b32_e32 v4, v2
	v_mov_b32_e32 v5, v2
	v_mov_b32_e32 v6, v2
	v_mov_b32_e32 v7, v2
	v_mov_b32_e32 v8, v2
	v_mov_b32_e32 v9, v2
	v_mov_b32_e32 v18, v2
	v_mov_b32_e32 v19, v2
	v_mov_b32_e32 v20, v2
	v_mov_b32_e32 v21, v2
	v_mov_b32_e32 v22, v2
	v_mov_b32_e32 v23, v2
	v_mov_b32_e32 v24, v2
	v_mov_b32_e32 v25, v2
	s_waitcnt vmcnt(0)
	v_mov_b64_e32 v[10:11], 0
	v_mov_b64_e32 v[12:13], 0
	v_mov_b64_e32 v[14:15], 0
	v_mov_b64_e32 v[16:17], 0
	v_mov_b64_e32 v[26:27], 0
	v_mov_b64_e32 v[28:29], 0
	v_mov_b64_e32 v[30:31], 0
	v_mov_b64_e32 v[32:33], 0
	v_mov_b64_e32 v[34:35], 0
	v_mov_b64_e32 v[36:37], 0
	v_mov_b64_e32 v[38:39], 0
	v_mov_b64_e32 v[40:41], 0
	v_mov_b64_e32 v[42:43], 0
	v_mov_b64_e32 v[44:45], 0
	v_mov_b64_e32 v[46:47], 0
	v_mov_b64_e32 v[48:49], 0
	v_mov_b64_e32 v[50:51], 0
	v_mov_b64_e32 v[52:53], 0
	v_mov_b64_e32 v[54:55], 0
	v_mov_b64_e32 v[56:57], 0
	v_mov_b64_e32 v[58:59], 0
	v_mov_b64_e32 v[60:61], 0
	v_mov_b64_e32 v[62:63], 0
	v_mov_b64_e32 v[64:65], 0
	v_mov_b64_e32 v[66:67], 0
	v_mov_b64_e32 v[68:69], 0
	v_mov_b64_e32 v[70:71], 0
	v_mov_b64_e32 v[72:73], 0
	v_mov_b64_e32 v[74:75], 0
	v_mov_b64_e32 v[76:77], 0
	v_mov_b64_e32 v[78:79], 0
	v_mov_b64_e32 v[80:81], 0
	v_mov_b64_e32 v[82:83], 0
	v_mov_b64_e32 v[84:85], 0
	v_mov_b64_e32 v[86:87], 0
	v_mov_b64_e32 v[88:89], 0
	v_mov_b64_e32 v[90:91], 0
	v_mov_b64_e32 v[92:93], 0
	v_mov_b64_e32 v[94:95], 0
	v_mov_b64_e32 v[96:97], 0
	v_mov_b64_e32 v[98:99], 0
	v_mov_b64_e32 v[100:101], 0
	v_mov_b64_e32 v[102:103], 0
	v_mov_b64_e32 v[104:105], 0
	v_mov_b64_e32 v[106:107], 0
	v_mov_b64_e32 v[108:109], 0
	v_mov_b64_e32 v[110:111], 0
	v_mov_b64_e32 v[112:113], 0
	v_mov_b64_e32 v[114:115], 0
	v_mov_b64_e32 v[116:117], 0
	v_mov_b64_e32 v[118:119], 0
	v_mov_b64_e32 v[120:121], 0
	v_mov_b64_e32 v[122:123], 0
	v_mov_b64_e32 v[124:125], 0
	v_mov_b64_e32 v[126:127], 0
	v_mov_b64_e32 v[128:129], 0

.LBB0_923:
	s_nop 8
	v_max_f32_e32 v163, v84, v85
	v_max3_f32 v163, v163, v86, v87
	v_max3_f32 v163, v163, v88, v89
	v_max3_f32 v163, v163, v90, v91
	v_max3_f32 v163, v163, v92, v93
	v_max3_f32 v163, v163, v94, v95
	v_max3_f32 v163, v163, v96, v97
	v_max3_f32 v163, v163, v98, v99
	v_max3_f32 v163, v163, v68, v69
	v_max3_f32 v163, v163, v70, v71
	v_max3_f32 v163, v163, v72, v73
	v_max3_f32 v163, v163, v74, v75
	v_max3_f32 v163, v163, v76, v77
	v_max3_f32 v163, v163, v78, v79
	v_max3_f32 v163, v163, v80, v81
	v_max3_f32 v163, v163, v82, v83
	v_mov_b32_e32 v164, v163
	s_nop 1
	v_permlane32_swap_b32_e32 v163, v164
	v_max_f32_e32 v164, v163, v164
	v_sub_f32_e32 v163, v164, v160
	v_cmp_ge_f32_e32 vcc, s91, v163
	s_cmp_eq_u64 vcc, exec
	v_mov_b32_e32 v163, 1.0
	s_cbranch_scc0 .LBB0_935

.LBB0_949:
	s_nop 8
	v_max_f32_e32 v165, v84, v85
	v_max3_f32 v165, v165, v86, v87
	v_max3_f32 v165, v165, v88, v89
	v_max3_f32 v165, v165, v90, v91
	v_max3_f32 v165, v165, v92, v93
	v_max3_f32 v165, v165, v94, v95
	v_max3_f32 v165, v165, v96, v97
	v_max3_f32 v165, v165, v98, v99
	v_max3_f32 v165, v165, v68, v69
	v_max3_f32 v165, v165, v70, v71
	v_max3_f32 v165, v165, v72, v73
	v_max3_f32 v165, v165, v74, v75
	v_max3_f32 v165, v165, v76, v77
	v_max3_f32 v165, v165, v78, v79
	v_max3_f32 v165, v165, v80, v81
	v_max3_f32 v165, v165, v82, v83
	v_mov_b32_e32 v166, v165
	s_nop 1
	v_permlane32_swap_b32_e32 v165, v166
	v_max_f32_e32 v166, v165, v166
	v_sub_f32_e32 v165, v166, v162
	v_cmp_ge_f32_e32 vcc, s91, v165
	s_cmp_eq_u64 vcc, exec
	v_mov_b32_e32 v165, 1.0
	s_cbranch_scc0 .LBB0_961

.LBB0_1216:
	s_ashr_i32 s15, s14, 31
	s_lshl_b64 s[16:17], s[14:15], 15
	v_readlane_b32 s5, v245, 53
	s_add_u32 s16, s5, s16
	v_readlane_b32 s5, v245, 56
	s_addc_u32 s17, s5, s17
	s_and_b64 s[18:19], s[10:11], exec
	s_cselect_b32 s5, s17, s23
	s_cselect_b32 s15, s16, s22
	s_ashr_i32 s13, s12, 31
	s_lshl_b64 s[18:19], s[12:13], 15
	v_readlane_b32 s24, v245, 4
	v_readlane_b32 s25, v245, 5
	s_add_u32 s18, s24, s18
	s_addc_u32 s19, s25, s19
	s_and_b64 s[24:25], s[10:11], exec
	s_cselect_b32 s13, s19, s21
	s_cselect_b32 s40, s18, s20
	s_add_u32 s41, s20, 0x100000
	s_addc_u32 s42, s21, 0
	s_add_u32 s20, s22, 0x104000
	v_mov_b32_e32 v2, 0
	s_addc_u32 s21, s23, 0
	s_mov_b32 s43, -2
	v_mov_b32_e32 v3, 0
	v_mov_b64_e32 v[4:5], 0
	v_mov_b64_e32 v[6:7], 0
	v_mov_b64_e32 v[8:9], 0
	v_mov_b64_e32 v[10:11], 0
	v_mov_b64_e32 v[12:13], 0
	v_mov_b64_e32 v[14:15], 0
	v_mov_b64_e32 v[16:17], 0
	v_mov_b64_e32 v[18:19], 0
	v_mov_b64_e32 v[20:21], 0
	v_mov_b64_e32 v[22:23], 0
	v_mov_b64_e32 v[24:25], 0
	v_mov_b64_e32 v[26:27], 0
	v_mov_b64_e32 v[28:29], 0
	v_mov_b64_e32 v[30:31], 0
	v_mov_b64_e32 v[32:33], 0
	v_mov_b64_e32 v[34:35], 0
	v_mov_b64_e32 v[36:37], 0
	v_mov_b64_e32 v[38:39], 0
	v_mov_b64_e32 v[40:41], 0
	v_mov_b64_e32 v[42:43], 0
	v_mov_b64_e32 v[44:45], 0
	v_mov_b64_e32 v[46:47], 0
	v_mov_b64_e32 v[48:49], 0
	v_mov_b64_e32 v[50:51], 0
	v_mov_b64_e32 v[52:53], 0
	v_mov_b64_e32 v[54:55], 0
	v_mov_b64_e32 v[56:57], 0
	v_mov_b64_e32 v[58:59], 0
	v_mov_b64_e32 v[60:61], 0
	v_mov_b64_e32 v[62:63], 0
	v_mov_b64_e32 v[64:65], 0
	v_mov_b64_e32 v[66:67], 0
	v_mov_b64_e32 v[68:69], 0
	v_mov_b64_e32 v[70:71], 0
	v_mov_b64_e32 v[72:73], 0
	v_mov_b64_e32 v[74:75], 0
	v_mov_b64_e32 v[76:77], 0
	v_mov_b64_e32 v[78:79], 0
	v_mov_b64_e32 v[80:81], 0
	v_mov_b64_e32 v[82:83], 0
	v_mov_b64_e32 v[84:85], 0
	v_mov_b64_e32 v[86:87], 0
	v_mov_b64_e32 v[88:89], 0
	v_mov_b64_e32 v[90:91], 0
	v_mov_b64_e32 v[92:93], 0
	v_mov_b64_e32 v[94:95], 0
	v_mov_b64_e32 v[96:97], 0
	v_mov_b64_e32 v[98:99], 0
	v_mov_b64_e32 v[100:101], 0
	v_mov_b64_e32 v[102:103], 0
	v_mov_b64_e32 v[104:105], 0
	v_mov_b64_e32 v[106:107], 0
	v_mov_b64_e32 v[108:109], 0
	v_mov_b64_e32 v[110:111], 0
	v_mov_b64_e32 v[112:113], 0
	v_mov_b64_e32 v[114:115], 0
	v_mov_b64_e32 v[116:117], 0
	v_mov_b64_e32 v[118:119], 0
	v_mov_b64_e32 v[120:121], 0
	v_mov_b64_e32 v[122:123], 0
	v_mov_b64_e32 v[124:125], 0
	v_mov_b64_e32 v[126:127], 0
	v_mov_b64_e32 v[128:129], 0
	s_waitcnt lgkmcnt(0)

.LBB0_1669:
	v_and_b32_e32 v8, 48, v142
	v_lshlrev_b32_e32 v9, 6, v142
	s_movk_i32 s17, 0x3c0
	s_lshl_b32 s11, s11, 5
	v_and_or_b32 v8, v9, s17, v8
	v_lshlrev_b32_e32 v9, 2, v142
	s_and_b32 s23, s11, 0x60
	s_lshl_b32 s22, s16, 6
	s_lshl_b32 s16, s16, 13
	v_and_b32_e32 v9, 32, v9
	s_lshl_b32 s11, s23, 7
	v_bitop3_b32 v10, v8, s16, v9 bitop3:0xde
	s_add_u32 s16, s4, 0x20000
	s_addc_u32 s17, s5, 0
	v_bitop3_b32 v11, s11, v8, v9 bitop3:0xf6
	s_add_i32 m0, s1, 0x18000
	v_lshl_add_u64 v[8:9], s[16:17], 0, v[134:135]
	s_waitcnt vmcnt(2)
	s_barrier
	global_load_lds_dwordx4 v[8:9], off
	s_add_i32 m0, s1, 0x1a000
	v_lshl_add_u64 v[8:9], s[16:17], 0, v[130:131]
	s_add_u32 s16, s70, 0x208000
	s_addc_u32 s17, s71, 0
	s_add_i32 s24, s1, 0x8000
	global_load_lds_dwordx4 v[8:9], off
	v_lshl_add_u64 v[8:9], s[16:17], 0, v[136:137]
	s_mov_b32 m0, s24
	s_add_i32 s25, s1, 0xa000
	global_load_lds_dwordx4 v[8:9], off
	v_lshl_add_u64 v[8:9], s[16:17], 0, v[132:133]
	s_add_u32 s16, s4, 0x24000
	s_mov_b32 m0, s25
	s_addc_u32 s17, s5, 0
	global_load_lds_dwordx4 v[8:9], off
	s_add_i32 m0, s1, 0x1c000
	v_lshl_add_u64 v[8:9], s[16:17], 0, v[134:135]
	global_load_lds_dwordx4 v[8:9], off
	v_lshl_add_u64 v[8:9], s[16:17], 0, v[130:131]
	s_add_i32 m0, s1, 0x1e000
	s_add_u32 s6, s70, s6
	global_load_lds_dwordx4 v[8:9], off
	v_lshlrev_b32_e32 v8, 10, v6
	v_and_b32_e32 v8, 0xfffff800, v8
	s_addc_u32 s7, s71, s7
	v_lshl_add_u32 v5, v5, 7, v8
	v_and_b32_e32 v6, 1, v6
	s_add_u32 s26, s6, 0x3940000
	v_lshl_or_b32 v5, v6, 6, v5
	s_addc_u32 s27, s7, 0
	v_lshl_add_u32 v138, v7, 1, v5
	v_lshlrev_b32_e32 v5, 10, v2
	s_add_u32 s6, s70, 0x20c000
	v_and_b32_e32 v5, 0xfffff800, v5
	s_waitcnt vmcnt(6)
	s_addc_u32 s7, s71, 0
	v_lshl_add_u32 v3, v3, 7, v5
	v_and_b32_e32 v2, 1, v2
	s_add_i32 s31, 0, 0x10000
	s_add_i32 s34, 0, 0x14000
	s_add_i32 s36, 0, 0x18000
	s_add_i32 s38, 0, 0x1c000
	v_lshl_or_b32 v2, v2, 6, v3
	v_add_u32_e32 v143, s31, v11
	v_add_u32_e32 v144, s34, v11
	s_add_i32 s31, s31, s10
	s_add_i32 s34, s34, s10
	v_add_u32_e32 v146, s36, v11
	v_add_u32_e32 v147, s38, v11
	s_add_i32 s36, s36, s10
	s_add_i32 s38, s38, s10
	v_mov_b32_e32 v139, v135
	v_lshl_add_u32 v140, v4, 1, v2
	v_mov_b32_e32 v141, v135
	s_mov_b32 s28, -2
	v_add_u32_e32 v145, 0, v10
	s_add_i32 s29, s1, 0xc000
	s_add_i32 s30, s1, 0xe000
	s_add_i32 s33, s31, 0x2000
	s_add_i32 s35, s34, 0x2000
	s_add_i32 s37, s36, 0x2000
	s_add_i32 s39, s38, 0x2000
	v_mov_b32_e32 v2, v135
	v_mov_b32_e32 v3, v135
	v_mov_b32_e32 v4, v135
	v_mov_b32_e32 v5, v135
	v_mov_b32_e32 v6, v135
	v_mov_b32_e32 v7, v135
	v_mov_b32_e32 v8, v135
	v_mov_b32_e32 v9, v135
	v_mov_b32_e32 v10, v135
	v_mov_b32_e32 v11, v135
	v_mov_b32_e32 v12, v135
	v_mov_b32_e32 v13, v135
	v_mov_b32_e32 v18, v135
	v_mov_b32_e32 v19, v135
	v_mov_b32_e32 v20, v135
	v_mov_b32_e32 v21, v135
	v_mov_b32_e32 v26, v135
	v_mov_b32_e32 v27, v135
	v_mov_b32_e32 v28, v135
	v_mov_b32_e32 v29, v135
	s_waitcnt vmcnt(0)
	v_mov_b64_e32 v[14:15], 0
	v_mov_b64_e32 v[16:17], 0
	v_mov_b64_e32 v[22:23], 0
	v_mov_b64_e32 v[24:25], 0
	v_mov_b64_e32 v[30:31], 0
	v_mov_b64_e32 v[32:33], 0
	v_mov_b64_e32 v[34:35], 0
	v_mov_b64_e32 v[36:37], 0
	v_mov_b64_e32 v[38:39], 0
	v_mov_b64_e32 v[40:41], 0
	v_mov_b64_e32 v[42:43], 0
	v_mov_b64_e32 v[44:45], 0
	v_mov_b64_e32 v[46:47], 0
	v_mov_b64_e32 v[48:49], 0
	v_mov_b64_e32 v[50:51], 0
	v_mov_b64_e32 v[52:53], 0
	v_mov_b64_e32 v[54:55], 0
	v_mov_b64_e32 v[56:57], 0
	v_mov_b64_e32 v[58:59], 0
	v_mov_b64_e32 v[60:61], 0
	v_mov_b64_e32 v[62:63], 0
	v_mov_b64_e32 v[64:65], 0
	v_mov_b64_e32 v[66:67], 0
	v_mov_b64_e32 v[68:69], 0
	v_mov_b64_e32 v[70:71], 0
	v_mov_b64_e32 v[72:73], 0
	v_mov_b64_e32 v[74:75], 0
	v_mov_b64_e32 v[76:77], 0
	v_mov_b64_e32 v[78:79], 0
	v_mov_b64_e32 v[80:81], 0
	v_mov_b64_e32 v[82:83], 0
	v_mov_b64_e32 v[84:85], 0
	v_mov_b64_e32 v[86:87], 0
	v_mov_b64_e32 v[88:89], 0
	v_mov_b64_e32 v[90:91], 0
	v_mov_b64_e32 v[92:93], 0
	v_mov_b64_e32 v[94:95], 0
	v_mov_b64_e32 v[96:97], 0
	v_mov_b64_e32 v[98:99], 0
	v_mov_b64_e32 v[100:101], 0
	v_mov_b64_e32 v[102:103], 0
	v_mov_b64_e32 v[104:105], 0
	v_mov_b64_e32 v[106:107], 0
	v_mov_b64_e32 v[108:109], 0
	v_mov_b64_e32 v[110:111], 0
	v_mov_b64_e32 v[112:113], 0
	v_mov_b64_e32 v[114:115], 0
	v_mov_b64_e32 v[116:117], 0
	v_mov_b64_e32 v[118:119], 0
	v_mov_b64_e32 v[120:121], 0
	v_mov_b64_e32 v[122:123], 0
	v_mov_b64_e32 v[124:125], 0
	v_mov_b64_e32 v[126:127], 0
	v_mov_b64_e32 v[128:129], 0
	s_barrier

.LBB0_1690:
	s_ashr_i32 s17, s16, 31
	v_cmp_lt_i64_e64 s[26:27], s[18:19], 64
	s_lshl_b64 s[18:19], s[16:17], 15
	v_readlane_b32 s7, v245, 12
	s_add_u32 s18, s7, s18
	v_readlane_b32 s7, v245, 13
	s_addc_u32 s19, s7, s19
	s_and_b64 s[20:21], s[26:27], exec
	s_cselect_b32 s11, s19, s25
	s_cselect_b32 s17, s18, s24
	s_ashr_i32 s7, s6, 31
	s_lshl_b64 s[20:21], s[6:7], 15
	s_add_u32 s20, s92, s20
	s_addc_u32 s21, s93, s21
	s_and_b64 s[26:27], s[26:27], exec
	s_cselect_b32 s7, s21, s23
	s_cselect_b32 s43, s20, s22
	s_add_u32 s44, s22, 0x20000
	s_addc_u32 s45, s23, 0
	s_add_u32 s22, s24, 0x104000
	v_mov_b32_e32 v2, 0
	s_addc_u32 s23, s25, 0
	s_mov_b32 s46, -2
	v_mov_b32_e32 v3, v2
	v_mov_b32_e32 v4, v2
	v_mov_b32_e32 v5, v2
	v_mov_b32_e32 v6, v2
	v_mov_b32_e32 v7, v2
	v_mov_b32_e32 v8, v2
	v_mov_b32_e32 v9, v2
	v_mov_b32_e32 v18, v2
	v_mov_b32_e32 v19, v2
	v_mov_b32_e32 v20, v2
	v_mov_b32_e32 v21, v2
	v_mov_b32_e32 v22, v2
	v_mov_b32_e32 v23, v2
	v_mov_b32_e32 v24, v2
	v_mov_b32_e32 v25, v2
	s_waitcnt vmcnt(0)
	v_mov_b64_e32 v[10:11], 0
	v_mov_b64_e32 v[12:13], 0
	v_mov_b64_e32 v[14:15], 0
	v_mov_b64_e32 v[16:17], 0
	v_mov_b64_e32 v[26:27], 0
	v_mov_b64_e32 v[28:29], 0
	v_mov_b64_e32 v[30:31], 0
	v_mov_b64_e32 v[32:33], 0
	v_mov_b64_e32 v[34:35], 0
	v_mov_b64_e32 v[36:37], 0
	v_mov_b64_e32 v[38:39], 0
	v_mov_b64_e32 v[40:41], 0
	v_mov_b64_e32 v[42:43], 0
	v_mov_b64_e32 v[44:45], 0
	v_mov_b64_e32 v[46:47], 0
	v_mov_b64_e32 v[48:49], 0
	v_mov_b64_e32 v[50:51], 0
	v_mov_b64_e32 v[52:53], 0
	v_mov_b64_e32 v[54:55], 0
	v_mov_b64_e32 v[56:57], 0
	v_mov_b64_e32 v[58:59], 0
	v_mov_b64_e32 v[60:61], 0
	v_mov_b64_e32 v[62:63], 0
	v_mov_b64_e32 v[64:65], 0
	v_mov_b64_e32 v[66:67], 0
	v_mov_b64_e32 v[68:69], 0
	v_mov_b64_e32 v[70:71], 0
	v_mov_b64_e32 v[72:73], 0
	v_mov_b64_e32 v[74:75], 0
	v_mov_b64_e32 v[76:77], 0
	v_mov_b64_e32 v[78:79], 0
	v_mov_b64_e32 v[80:81], 0
	v_mov_b64_e32 v[82:83], 0
	v_mov_b64_e32 v[84:85], 0
	v_mov_b64_e32 v[86:87], 0
	v_mov_b64_e32 v[88:89], 0
	v_mov_b64_e32 v[90:91], 0
	v_mov_b64_e32 v[92:93], 0
	v_mov_b64_e32 v[94:95], 0
	v_mov_b64_e32 v[96:97], 0
	v_mov_b64_e32 v[98:99], 0
	v_mov_b64_e32 v[100:101], 0
	v_mov_b64_e32 v[102:103], 0
	v_mov_b64_e32 v[104:105], 0
	v_mov_b64_e32 v[106:107], 0
	v_mov_b64_e32 v[108:109], 0
	v_mov_b64_e32 v[110:111], 0
	v_mov_b64_e32 v[112:113], 0
	v_mov_b64_e32 v[114:115], 0
	v_mov_b64_e32 v[116:117], 0
	v_mov_b64_e32 v[118:119], 0
	v_mov_b64_e32 v[120:121], 0
	v_mov_b64_e32 v[122:123], 0
	v_mov_b64_e32 v[124:125], 0
	v_mov_b64_e32 v[126:127], 0
	v_mov_b64_e32 v[128:129], 0

.LBB0_1717:
	s_mov_b32 s20, s44
	s_add_i32 s44, s45, 1
	s_cmp_lt_u32 s45, 3
	s_cselect_b64 s[18:19], -1, 0
	s_and_b64 s[10:11], s[18:19], exec
	s_cselect_b32 s10, s44, s20
	s_ashr_i32 s11, s10, 31
	s_lshl_b64 s[10:11], s[10:11], 15
	v_readlane_b32 s20, v245, 0
	v_readlane_b32 s21, v245, 1
	s_add_u32 s10, s20, s10
	s_addc_u32 s11, s21, s11
	s_and_b64 s[18:19], s[18:19], exec
	s_cselect_b32 s46, s11, s17
	s_cselect_b32 s47, s10, s16
	s_add_u32 s48, s16, 0x40000
	v_mov_b32_e32 v2, 0
	s_addc_u32 s49, s17, 0
	s_mov_b32 s50, -2
	s_mov_b64 s[16:17], s[2:3]
	v_mov_b32_e32 v3, 0
	v_mov_b64_e32 v[4:5], 0
	v_mov_b64_e32 v[6:7], 0
	v_mov_b64_e32 v[8:9], 0
	v_mov_b64_e32 v[10:11], 0
	v_mov_b64_e32 v[12:13], 0
	v_mov_b64_e32 v[14:15], 0
	v_mov_b64_e32 v[16:17], 0
	v_mov_b64_e32 v[18:19], 0
	v_mov_b64_e32 v[20:21], 0
	v_mov_b64_e32 v[22:23], 0
	v_mov_b64_e32 v[24:25], 0
	v_mov_b64_e32 v[26:27], 0
	v_mov_b64_e32 v[28:29], 0
	v_mov_b64_e32 v[30:31], 0
	v_mov_b64_e32 v[32:33], 0
	v_mov_b64_e32 v[34:35], 0
	v_mov_b64_e32 v[36:37], 0
	v_mov_b64_e32 v[38:39], 0
	v_mov_b64_e32 v[40:41], 0
	v_mov_b64_e32 v[42:43], 0
	v_mov_b64_e32 v[44:45], 0
	v_mov_b64_e32 v[46:47], 0
	v_mov_b64_e32 v[48:49], 0
	v_mov_b64_e32 v[50:51], 0
	v_mov_b64_e32 v[52:53], 0
	v_mov_b64_e32 v[54:55], 0
	v_mov_b64_e32 v[56:57], 0
	v_mov_b64_e32 v[58:59], 0
	v_mov_b64_e32 v[60:61], 0
	v_mov_b64_e32 v[62:63], 0
	v_mov_b64_e32 v[64:65], 0
	v_mov_b64_e32 v[66:67], 0
	v_mov_b64_e32 v[68:69], 0
	v_mov_b64_e32 v[70:71], 0
	v_mov_b64_e32 v[72:73], 0
	v_mov_b64_e32 v[74:75], 0
	v_mov_b64_e32 v[76:77], 0
	v_mov_b64_e32 v[78:79], 0
	v_mov_b64_e32 v[80:81], 0
	v_mov_b64_e32 v[82:83], 0
	v_mov_b64_e32 v[84:85], 0
	v_mov_b64_e32 v[86:87], 0
	v_mov_b64_e32 v[88:89], 0
	v_mov_b64_e32 v[90:91], 0
	v_mov_b64_e32 v[92:93], 0
	v_mov_b64_e32 v[94:95], 0
	v_mov_b64_e32 v[96:97], 0
	v_mov_b64_e32 v[98:99], 0
	v_mov_b64_e32 v[100:101], 0
	v_mov_b64_e32 v[102:103], 0
	v_mov_b64_e32 v[104:105], 0
	v_mov_b64_e32 v[106:107], 0
	v_mov_b64_e32 v[108:109], 0
	v_mov_b64_e32 v[110:111], 0
	v_mov_b64_e32 v[112:113], 0
	v_mov_b64_e32 v[114:115], 0
	v_mov_b64_e32 v[116:117], 0
	v_mov_b64_e32 v[118:119], 0
	v_mov_b64_e32 v[120:121], 0
	v_mov_b64_e32 v[122:123], 0
	v_mov_b64_e32 v[124:125], 0
	v_mov_b64_e32 v[126:127], 0
	v_mov_b64_e32 v[128:129], 0

.LBB0_1942:
	v_add_u32_e32 v195, 0, v189
	v_add_u32_e32 v70, 0x1c000, v195
	ds_read_b128 v[66:69], v70 offset:0
	ds_read_b128 v[82:85], v70 offset:0x2000
	v_add_u32_e32 v196, 0, v188
	v_add_u32_e32 v70, 0x1c000, v196
	ds_read_b128 v[86:89], v70 offset:0
	ds_read_b128 v[212:215], v70 offset:0x2000
	v_add_u32_e32 v197, 0, v187
	v_add_u32_e32 v70, 0x1c000, v197
	ds_read_b128 v[90:93], v70 offset:0
	ds_read_b128 v[220:223], v70 offset:0x2000
	v_add_u32_e32 v198, 0, v186
	v_add_u32_e32 v70, 0x1c000, v198
	ds_read_b128 v[94:97], v70 offset:0
	ds_read_b128 v[224:227], v70 offset:0x2000
	s_waitcnt lgkmcnt(4)
	v_mfma_f32_32x32x16_bf16 v[66:81], v[66:69], v[98:101], 0
	s_nop 0
	v_mfma_f32_32x32x16_bf16 v[66:81], v[86:89], v[102:105], v[66:81]
	s_waitcnt lgkmcnt(0)
	v_mfma_f32_32x32x16_bf16 v[66:81], v[90:93], v[106:109], v[66:81]
	v_add_u32_e32 v199, 0, v185
	v_add_u32_e32 v130, 0x1c000, v199
	ds_read_b128 v[86:89], v130 offset:0
	ds_read_b128 v[228:231], v130 offset:0x2000
	v_add_u32_e32 v200, 0, v184
	v_add_u32_e32 v130, 0x1c000, v200
	ds_read_b128 v[90:93], v130 offset:0
	ds_read_b128 v[232:235], v130 offset:0x2000
	v_add_u32_e32 v202, 0, v183
	v_mfma_f32_32x32x16_bf16 v[66:81], v[94:97], v[110:113], v[66:81]
	v_add_u32_e32 v134, 0x1c000, v202
	ds_read_b128 v[130:133], v134 offset:0
	ds_read_b128 v[236:239], v134 offset:0x2000
	v_add_u32_e32 v203, 0, v182
	v_add_u32_e32 v134, 0x1c000, v203
	ds_read_b128 v[94:97], v134 offset:0
	ds_read_b128 v[240:243], v134 offset:0x2000
	s_waitcnt lgkmcnt(4)
	v_mfma_f32_32x32x16_bf16 v[66:81], v[86:89], v[114:117], v[66:81]
	v_mfma_f32_32x32x16_bf16 v[66:81], v[90:93], v[118:121], v[66:81]
	s_waitcnt lgkmcnt(0)
	v_mfma_f32_32x32x16_bf16 v[66:81], v[130:133], v[122:125], v[66:81]
	v_mfma_f32_32x32x16_bf16 v[66:81], v[94:97], v[126:129], v[66:81]
	v_add_u32_e32 v204, 0, v181
	v_add_u32_e32 v206, 0xc000, v204
	ds_read_b64_tr_b16 v[158:159], v206 offset:0
	ds_read_b64_tr_b16 v[160:161], v206 offset:0x800
	ds_read_b64_tr_b16 v[154:155], v206 offset:0x1000
	ds_read_b64_tr_b16 v[156:157], v206 offset:0x1800
	ds_read_b64_tr_b16 v[150:151], v206 offset:0x2000
	ds_read_b64_tr_b16 v[152:153], v206 offset:0x2800
	ds_read_b64_tr_b16 v[146:147], v206 offset:0x3000
	ds_read_b64_tr_b16 v[148:149], v206 offset:0x3800
	ds_read_b64_tr_b16 v[142:143], v206 offset:0x200
	ds_read_b64_tr_b16 v[144:145], v206 offset:0xa00
	ds_read_b64_tr_b16 v[138:139], v206 offset:0x1200
	ds_read_b64_tr_b16 v[140:141], v206 offset:0x1a00
	ds_read_b64_tr_b16 v[134:135], v206 offset:0x2200
	ds_read_b64_tr_b16 v[136:137], v206 offset:0x2a00
	ds_read_b64_tr_b16 v[130:131], v206 offset:0x3200
	ds_read_b64_tr_b16 v[132:133], v206 offset:0x3a00
	v_mfma_f32_32x32x16_bf16 v[82:97], v[82:85], v[98:101], 0
	s_nop 8
	v_max_f32_e32 v192, v66, v67
	v_max3_f32 v192, v192, v68, v69
	v_max3_f32 v192, v192, v70, v71
	v_max3_f32 v192, v192, v72, v73
	v_max3_f32 v192, v192, v74, v75
	v_mfma_f32_32x32x16_bf16 v[82:97], v[212:215], v[102:105], v[82:97]
	v_max3_f32 v192, v192, v76, v77
	v_max3_f32 v192, v192, v78, v79
	v_max3_f32 v192, v192, v80, v81
	v_mfma_f32_32x32x16_bf16 v[82:97], v[220:223], v[106:109], v[82:97]
	v_mfma_f32_32x32x16_bf16 v[82:97], v[224:227], v[110:113], v[82:97]
	v_mfma_f32_32x32x16_bf16 v[82:97], v[228:231], v[114:117], v[82:97]
	v_mfma_f32_32x32x16_bf16 v[82:97], v[232:235], v[118:121], v[82:97]
	v_mfma_f32_32x32x16_bf16 v[82:97], v[236:239], v[122:125], v[82:97]
	v_mfma_f32_32x32x16_bf16 v[82:97], v[240:243], v[126:129], v[82:97]
	s_nop 11
	v_max3_f32 v192, v192, v82, v83
	v_max3_f32 v192, v192, v84, v85
	v_max3_f32 v192, v192, v86, v87
	v_max3_f32 v192, v192, v88, v89
	v_max3_f32 v192, v192, v90, v91
	v_max3_f32 v192, v192, v92, v93
	v_max3_f32 v192, v192, v94, v95
	v_max3_f32 v192, v192, v96, v97
	v_mov_b32_e32 v193, v192
	s_nop 1
	v_permlane32_swap_b32_e32 v192, v193
	v_max_f32_e32 v193, v192, v193
	v_sub_f32_e32 v192, v193, v190
	v_cmp_ge_f32_e32 vcc, s30, v192
	s_cmp_eq_u64 vcc, exec
	v_mov_b32_e32 v192, 1.0
	s_cbranch_scc0 .LBB0_1951

.LBB0_1947:
	v_cvt_pk_bf16_f32 v212, v207, v208
	v_cvt_pk_bf16_f32 v213, v83, v84
	v_cvt_pk_bf16_f32 v214, v85, v86
	v_cvt_pk_bf16_f32 v215, v87, v209
	v_cvt_pk_bf16_f32 v84, v88, v89
	v_cvt_pk_bf16_f32 v85, v90, v91
	v_cvt_pk_bf16_f32 v86, v92, v93
	v_cvt_pk_bf16_f32 v87, v94, v81
	v_cvt_pk_bf16_f32 v66, v66, v67
	v_cvt_pk_bf16_f32 v67, v68, v69
	v_cvt_pk_bf16_f32 v68, v70, v71
	v_cvt_pk_bf16_f32 v69, v72, v82
	v_cvt_pk_bf16_f32 v70, v73, v74
	v_cvt_pk_bf16_f32 v71, v75, v76
	v_cvt_pk_bf16_f32 v72, v77, v78
	v_cvt_pk_bf16_f32 v73, v79, v80
	s_waitcnt lgkmcnt(0)
	s_nop 0
	v_mfma_f32_32x32x16_bf16 v[2:17], v[212:215], v[158:161], v[2:17]
	v_mfma_f32_32x32x16_bf16 v[2:17], v[84:87], v[154:157], v[2:17]
	v_mfma_f32_32x32x16_bf16 v[2:17], v[66:69], v[150:153], v[2:17]
	v_mfma_f32_32x32x16_bf16 v[2:17], v[70:73], v[146:149], v[2:17]
	ds_read_b64_tr_b16 v[74:75], v206 offset:0x400
	ds_read_b64_tr_b16 v[76:77], v206 offset:0xc00
	ds_read_b64_tr_b16 v[78:79], v206 offset:0x1400
	ds_read_b64_tr_b16 v[80:81], v206 offset:0x1c00
	ds_read_b64_tr_b16 v[88:89], v206 offset:0x2400
	ds_read_b64_tr_b16 v[90:91], v206 offset:0x2c00
	ds_read_b64_tr_b16 v[92:93], v206 offset:0x3400
	ds_read_b64_tr_b16 v[94:95], v206 offset:0x3c00
	v_mfma_f32_32x32x16_bf16 v[18:33], v[212:215], v[142:145], v[18:33]
	v_mfma_f32_32x32x16_bf16 v[18:33], v[84:87], v[138:141], v[18:33]
	v_mfma_f32_32x32x16_bf16 v[18:33], v[66:69], v[134:137], v[18:33]
	v_mfma_f32_32x32x16_bf16 v[18:33], v[70:73], v[130:133], v[18:33]
	ds_read_b64_tr_b16 v[130:131], v206 offset:0x600
	ds_read_b64_tr_b16 v[132:133], v206 offset:0xe00
	ds_read_b64_tr_b16 v[134:135], v206 offset:0x1600
	ds_read_b64_tr_b16 v[136:137], v206 offset:0x1e00
	ds_read_b64_tr_b16 v[138:139], v206 offset:0x2600
	ds_read_b64_tr_b16 v[140:141], v206 offset:0x2e00
	ds_read_b64_tr_b16 v[142:143], v206 offset:0x3600
	ds_read_b64_tr_b16 v[144:145], v206 offset:0x3e00
	s_waitcnt lgkmcnt(8)
	v_mfma_f32_32x32x16_bf16 v[34:49], v[212:215], v[74:77], v[34:49]
	v_mfma_f32_32x32x16_bf16 v[34:49], v[84:87], v[78:81], v[34:49]
	v_mfma_f32_32x32x16_bf16 v[34:49], v[66:69], v[88:91], v[34:49]
	v_mfma_f32_32x32x16_bf16 v[34:49], v[70:73], v[92:95], v[34:49]
	s_waitcnt lgkmcnt(0)
	v_mfma_f32_32x32x16_bf16 v[50:65], v[212:215], v[130:133], v[50:65]
	v_add_u32_e32 v78, 0x18000, v195
	ds_read_b128 v[74:77], v78 offset:0
	v_mfma_f32_32x32x16_bf16 v[50:65], v[84:87], v[134:137], v[50:65]
	ds_read_b128 v[82:85], v78 offset:0x2000
	v_add_u32_e32 v78, 0x18000, v196
	ds_read_b128 v[86:89], v78 offset:0
	ds_read_b128 v[206:209], v78 offset:0x2000
	v_mfma_f32_32x32x16_bf16 v[50:65], v[66:69], v[138:141], v[50:65]
	v_add_u32_e32 v66, 0x18000, v197
	ds_read_b128 v[90:93], v66 offset:0
	ds_read_b128 v[212:215], v66 offset:0x2000
	v_add_u32_e32 v66, 0x18000, v198
	ds_read_b128 v[94:97], v66 offset:0
	ds_read_b128 v[220:223], v66 offset:0x2000
	s_waitcnt lgkmcnt(4)
	v_mfma_f32_32x32x16_bf16 v[50:65], v[70:73], v[142:145], v[50:65]
	v_mfma_f32_32x32x16_bf16 v[66:81], v[74:77], v[98:101], 0
	v_mfma_f32_32x32x16_bf16 v[66:81], v[86:89], v[102:105], v[66:81]
	s_waitcnt lgkmcnt(0)
	v_mfma_f32_32x32x16_bf16 v[66:81], v[90:93], v[106:109], v[66:81]
	v_add_u32_e32 v130, 0x18000, v199
	ds_read_b128 v[86:89], v130 offset:0
	ds_read_b128 v[196:199], v130 offset:0x2000
	v_add_u32_e32 v134, 0x18000, v200
	ds_read_b128 v[130:133], v134 offset:0
	ds_read_b128 v[224:227], v134 offset:0x2000
	v_add_u32_e32 v134, 0x18000, v202
	v_mfma_f32_32x32x16_bf16 v[66:81], v[94:97], v[110:113], v[66:81]
	ds_read_b128 v[90:93], v134 offset:0
	ds_read_b128 v[228:231], v134 offset:0x2000
	v_add_u32_e32 v138, 0x18000, v203
	ds_read_b128 v[134:137], v138 offset:0
	ds_read_b128 v[232:235], v138 offset:0x2000
	s_waitcnt lgkmcnt(4)
	v_mfma_f32_32x32x16_bf16 v[66:81], v[86:89], v[114:117], v[66:81]
	v_mfma_f32_32x32x16_bf16 v[66:81], v[130:133], v[118:121], v[66:81]
	s_waitcnt lgkmcnt(0)
	v_mfma_f32_32x32x16_bf16 v[66:81], v[90:93], v[122:125], v[66:81]
	v_mfma_f32_32x32x16_bf16 v[66:81], v[134:137], v[126:129], v[66:81]
	v_add_u32_e32 v195, 0x8000, v204
	ds_read_b64_tr_b16 v[158:159], v195 offset:0
	ds_read_b64_tr_b16 v[160:161], v195 offset:0x800
	ds_read_b64_tr_b16 v[154:155], v195 offset:0x1000
	ds_read_b64_tr_b16 v[156:157], v195 offset:0x1800
	ds_read_b64_tr_b16 v[150:151], v195 offset:0x2000
	ds_read_b64_tr_b16 v[152:153], v195 offset:0x2800
	ds_read_b64_tr_b16 v[146:147], v195 offset:0x3000
	ds_read_b64_tr_b16 v[148:149], v195 offset:0x3800
	ds_read_b64_tr_b16 v[142:143], v195 offset:0x200
	ds_read_b64_tr_b16 v[144:145], v195 offset:0xa00
	ds_read_b64_tr_b16 v[138:139], v195 offset:0x1200
	ds_read_b64_tr_b16 v[140:141], v195 offset:0x1a00
	ds_read_b64_tr_b16 v[134:135], v195 offset:0x2200
	ds_read_b64_tr_b16 v[136:137], v195 offset:0x2a00
	ds_read_b64_tr_b16 v[130:131], v195 offset:0x3200
	ds_read_b64_tr_b16 v[132:133], v195 offset:0x3a00
	v_mfma_f32_32x32x16_bf16 v[82:97], v[82:85], v[98:101], 0
	v_mfma_f32_32x32x16_bf16 v[82:97], v[206:209], v[102:105], v[82:97]
	v_mfma_f32_32x32x16_bf16 v[82:97], v[212:215], v[106:109], v[82:97]
	v_mfma_f32_32x32x16_bf16 v[82:97], v[220:223], v[110:113], v[82:97]
	v_mfma_f32_32x32x16_bf16 v[82:97], v[196:199], v[114:117], v[82:97]
	s_nop 5
	v_max_f32_e32 v196, v66, v67
	v_max3_f32 v196, v196, v68, v69
	v_max3_f32 v196, v196, v70, v71
	v_max3_f32 v196, v196, v72, v73
	v_max3_f32 v196, v196, v74, v75
	v_mfma_f32_32x32x16_bf16 v[82:97], v[224:227], v[118:121], v[82:97]
	v_max3_f32 v196, v196, v76, v77
	v_max3_f32 v196, v196, v78, v79
	v_max3_f32 v196, v196, v80, v81
	v_mfma_f32_32x32x16_bf16 v[82:97], v[228:231], v[122:125], v[82:97]
	v_mfma_f32_32x32x16_bf16 v[82:97], v[232:235], v[126:129], v[82:97]
	s_nop 11
	v_max3_f32 v196, v196, v82, v83
	v_max3_f32 v196, v196, v84, v85
	v_max3_f32 v196, v196, v86, v87
	v_max3_f32 v196, v196, v88, v89
	v_max3_f32 v196, v196, v90, v91
	v_max3_f32 v196, v196, v92, v93
	v_max3_f32 v196, v196, v94, v95
	v_max3_f32 v196, v196, v96, v97
	v_mov_b32_e32 v197, v196
	s_nop 1
	v_permlane32_swap_b32_e32 v196, v197
	v_max_f32_e32 v197, v196, v197
	v_sub_f32_e32 v196, v197, v190
	v_cmp_ge_f32_e32 vcc, s30, v196
	s_cmp_eq_u64 vcc, exec
	v_mov_b32_e32 v196, 1.0
	s_cbranch_scc0 .LBB0_1952

.LBB0_2184:
	s_ashr_i32 s15, s14, 31
	s_lshl_b64 s[16:17], s[14:15], 15
	s_add_u32 s16, s33, s16
	s_addc_u32 s17, s58, s17
	s_and_b64 s[18:19], s[10:11], exec
	s_cselect_b32 s5, s17, s23
	s_cselect_b32 s15, s16, s22
	s_ashr_i32 s13, s12, 31
	s_lshl_b64 s[18:19], s[12:13], 15
	v_readlane_b32 s24, v245, 2
	v_readlane_b32 s25, v245, 3
	s_add_u32 s18, s24, s18
	s_addc_u32 s19, s25, s19
	s_and_b64 s[24:25], s[10:11], exec
	s_cselect_b32 s13, s19, s21
	s_cselect_b32 s41, s18, s20
	s_add_u32 s42, s20, 0x100000
	s_addc_u32 s43, s21, 0
	s_add_u32 s20, s22, 0x104000
	v_mov_b32_e32 v2, 0
	s_addc_u32 s21, s23, 0
	s_mov_b32 s44, -2
	v_mov_b32_e32 v3, 0
	v_mov_b64_e32 v[4:5], 0
	v_mov_b64_e32 v[6:7], 0
	v_mov_b64_e32 v[8:9], 0
	v_mov_b64_e32 v[10:11], 0
	v_mov_b64_e32 v[12:13], 0
	v_mov_b64_e32 v[14:15], 0
	v_mov_b64_e32 v[16:17], 0
	v_mov_b64_e32 v[18:19], 0
	v_mov_b64_e32 v[20:21], 0
	v_mov_b64_e32 v[22:23], 0
	v_mov_b64_e32 v[24:25], 0
	v_mov_b64_e32 v[26:27], 0
	v_mov_b64_e32 v[28:29], 0
	v_mov_b64_e32 v[30:31], 0
	v_mov_b64_e32 v[32:33], 0
	v_mov_b64_e32 v[34:35], 0
	v_mov_b64_e32 v[36:37], 0
	v_mov_b64_e32 v[38:39], 0
	v_mov_b64_e32 v[40:41], 0
	v_mov_b64_e32 v[42:43], 0
	v_mov_b64_e32 v[44:45], 0
	v_mov_b64_e32 v[46:47], 0
	v_mov_b64_e32 v[48:49], 0
	v_mov_b64_e32 v[50:51], 0
	v_mov_b64_e32 v[52:53], 0
	v_mov_b64_e32 v[54:55], 0
	v_mov_b64_e32 v[56:57], 0
	v_mov_b64_e32 v[58:59], 0
	v_mov_b64_e32 v[60:61], 0
	v_mov_b64_e32 v[62:63], 0
	v_mov_b64_e32 v[64:65], 0
	v_mov_b64_e32 v[66:67], 0
	v_mov_b64_e32 v[68:69], 0
	v_mov_b64_e32 v[70:71], 0
	v_mov_b64_e32 v[72:73], 0
	v_mov_b64_e32 v[74:75], 0
	v_mov_b64_e32 v[76:77], 0
	v_mov_b64_e32 v[78:79], 0
	v_mov_b64_e32 v[80:81], 0
	v_mov_b64_e32 v[82:83], 0
	v_mov_b64_e32 v[84:85], 0
	v_mov_b64_e32 v[86:87], 0
	v_mov_b64_e32 v[88:89], 0
	v_mov_b64_e32 v[90:91], 0
	v_mov_b64_e32 v[92:93], 0
	v_mov_b64_e32 v[94:95], 0
	v_mov_b64_e32 v[96:97], 0
	v_mov_b64_e32 v[98:99], 0
	v_mov_b64_e32 v[100:101], 0
	v_mov_b64_e32 v[102:103], 0
	v_mov_b64_e32 v[104:105], 0
	v_mov_b64_e32 v[106:107], 0
	v_mov_b64_e32 v[108:109], 0
	v_mov_b64_e32 v[110:111], 0
	v_mov_b64_e32 v[112:113], 0
	v_mov_b64_e32 v[114:115], 0
	v_mov_b64_e32 v[116:117], 0
	v_mov_b64_e32 v[118:119], 0
	v_mov_b64_e32 v[120:121], 0
	v_mov_b64_e32 v[122:123], 0
	v_mov_b64_e32 v[124:125], 0
	v_mov_b64_e32 v[126:127], 0
	v_mov_b64_e32 v[128:129], 0
	s_waitcnt lgkmcnt(0)

.LBB0_2479:
	s_ashr_i32 s17, s16, 31
	s_lshl_b64 s[18:19], s[16:17], 15
	s_add_u32 s18, s1, s18
	s_addc_u32 s19, s13, s19
	s_and_b64 s[20:21], s[10:11], exec
	s_cselect_b32 s5, s19, s27
	s_cselect_b32 s17, s18, s26
	s_ashr_i32 s15, s14, 31
	s_lshl_b64 s[20:21], s[14:15], 15
	v_readlane_b32 s28, v245, 10
	v_readlane_b32 s29, v245, 11
	s_add_u32 s20, s28, s20
	s_addc_u32 s21, s29, s21
	s_and_b64 s[28:29], s[10:11], exec
	s_cselect_b32 s15, s21, s25
	s_cselect_b32 s23, s20, s24
	s_add_u32 s46, s24, 0x700000
	s_addc_u32 s47, s25, 0
	s_add_u32 s24, s26, 0x104000
	v_mov_b32_e32 v34, 0
	s_addc_u32 s25, s27, 0
	s_mov_b32 s48, -2
	v_mov_b32_e32 v35, 0
	v_mov_b64_e32 v[36:37], 0
	v_mov_b64_e32 v[38:39], 0
	v_mov_b64_e32 v[40:41], 0
	v_mov_b64_e32 v[42:43], 0
	v_mov_b64_e32 v[44:45], 0
	v_mov_b64_e32 v[46:47], 0
	v_mov_b64_e32 v[48:49], 0
	v_mov_b64_e32 v[50:51], 0
	v_mov_b64_e32 v[52:53], 0
	v_mov_b64_e32 v[54:55], 0
	v_mov_b64_e32 v[56:57], 0
	v_mov_b64_e32 v[58:59], 0
	v_mov_b64_e32 v[60:61], 0
	v_mov_b64_e32 v[62:63], 0
	v_mov_b64_e32 v[64:65], 0
	v_mov_b64_e32 v[66:67], 0
	v_mov_b64_e32 v[68:69], 0
	v_mov_b64_e32 v[70:71], 0
	v_mov_b64_e32 v[72:73], 0
	v_mov_b64_e32 v[74:75], 0
	v_mov_b64_e32 v[76:77], 0
	v_mov_b64_e32 v[78:79], 0
	v_mov_b64_e32 v[80:81], 0
	v_mov_b64_e32 v[82:83], 0
	v_mov_b64_e32 v[84:85], 0
	v_mov_b64_e32 v[86:87], 0
	v_mov_b64_e32 v[88:89], 0
	v_mov_b64_e32 v[90:91], 0
	v_mov_b64_e32 v[92:93], 0
	v_mov_b64_e32 v[94:95], 0
	v_mov_b64_e32 v[96:97], 0
	v_mov_b64_e32 v[98:99], 0
	v_mov_b64_e32 v[100:101], 0
	v_mov_b64_e32 v[102:103], 0
	v_mov_b64_e32 v[104:105], 0
	v_mov_b64_e32 v[106:107], 0
	v_mov_b64_e32 v[108:109], 0
	v_mov_b64_e32 v[110:111], 0
	v_mov_b64_e32 v[112:113], 0
	v_mov_b64_e32 v[114:115], 0
	v_mov_b64_e32 v[116:117], 0
	v_mov_b64_e32 v[118:119], 0
	v_mov_b64_e32 v[120:121], 0
	v_mov_b64_e32 v[122:123], 0
	v_mov_b64_e32 v[124:125], 0
	v_mov_b64_e32 v[126:127], 0
	v_mov_b64_e32 v[128:129], 0
	v_mov_b64_e32 v[130:131], 0
	v_mov_b64_e32 v[132:133], 0
	v_mov_b64_e32 v[134:135], 0
	v_mov_b64_e32 v[136:137], 0
	v_mov_b64_e32 v[138:139], 0
	v_mov_b64_e32 v[140:141], 0
	v_mov_b64_e32 v[142:143], 0
	v_mov_b64_e32 v[144:145], 0
	v_mov_b64_e32 v[146:147], 0
	v_mov_b64_e32 v[148:149], 0
	v_mov_b64_e32 v[150:151], 0
	v_mov_b64_e32 v[152:153], 0
	v_mov_b64_e32 v[154:155], 0
	v_mov_b64_e32 v[156:157], 0
	v_mov_b64_e32 v[158:159], 0
	v_mov_b64_e32 v[160:161], 0

.LBB0_2713:
	s_ashr_i32 s17, s16, 31
	s_lshl_b64 s[18:19], s[16:17], 15
	v_readlane_b32 s20, v245, 14
	v_readlane_b32 s21, v245, 15
	s_add_u32 s18, s20, s18
	s_addc_u32 s19, s21, s19
	s_and_b64 s[20:21], s[8:9], exec
	s_cselect_b32 s5, s19, s25
	s_cselect_b32 s17, s18, s24
	s_ashr_i32 s15, s14, 31
	s_lshl_b64 s[20:21], s[14:15], 15
	s_add_u32 s20, s88, s20
	s_addc_u32 s21, s89, s21
	s_and_b64 s[26:27], s[8:9], exec
	s_cselect_b32 s15, s21, s23
	s_cselect_b32 s41, s20, s22
	s_add_u32 s42, s22, 0x100000
	s_addc_u32 s43, s23, 0
	s_add_u32 s22, s24, 0x104000
	v_mov_b32_e32 v34, 0
	s_addc_u32 s23, s25, 0
	s_mov_b32 s44, -2
	v_mov_b32_e32 v35, 0
	v_mov_b64_e32 v[36:37], 0
	v_mov_b64_e32 v[38:39], 0
	v_mov_b64_e32 v[40:41], 0
	v_mov_b64_e32 v[42:43], 0
	v_mov_b64_e32 v[44:45], 0
	v_mov_b64_e32 v[46:47], 0
	v_mov_b64_e32 v[48:49], 0
	v_mov_b64_e32 v[50:51], 0
	v_mov_b64_e32 v[52:53], 0
	v_mov_b64_e32 v[54:55], 0
	v_mov_b64_e32 v[56:57], 0
	v_mov_b64_e32 v[58:59], 0
	v_mov_b64_e32 v[60:61], 0
	v_mov_b64_e32 v[62:63], 0
	v_mov_b64_e32 v[64:65], 0
	v_mov_b64_e32 v[66:67], 0
	v_mov_b64_e32 v[68:69], 0
	v_mov_b64_e32 v[70:71], 0
	v_mov_b64_e32 v[72:73], 0
	v_mov_b64_e32 v[74:75], 0
	v_mov_b64_e32 v[76:77], 0
	v_mov_b64_e32 v[78:79], 0
	v_mov_b64_e32 v[80:81], 0
	v_mov_b64_e32 v[82:83], 0
	v_mov_b64_e32 v[84:85], 0
	v_mov_b64_e32 v[86:87], 0
	v_mov_b64_e32 v[88:89], 0
	v_mov_b64_e32 v[90:91], 0
	v_mov_b64_e32 v[92:93], 0
	v_mov_b64_e32 v[94:95], 0
	v_mov_b64_e32 v[96:97], 0
	v_mov_b64_e32 v[98:99], 0
	v_mov_b64_e32 v[100:101], 0
	v_mov_b64_e32 v[102:103], 0
	v_mov_b64_e32 v[104:105], 0
	v_mov_b64_e32 v[106:107], 0
	v_mov_b64_e32 v[108:109], 0
	v_mov_b64_e32 v[110:111], 0
	v_mov_b64_e32 v[112:113], 0
	v_mov_b64_e32 v[114:115], 0
	v_mov_b64_e32 v[116:117], 0
	v_mov_b64_e32 v[118:119], 0
	v_mov_b64_e32 v[120:121], 0
	v_mov_b64_e32 v[122:123], 0
	v_mov_b64_e32 v[124:125], 0
	v_mov_b64_e32 v[126:127], 0
	v_mov_b64_e32 v[128:129], 0
	v_mov_b64_e32 v[130:131], 0
	v_mov_b64_e32 v[132:133], 0
	v_mov_b64_e32 v[134:135], 0
	v_mov_b64_e32 v[136:137], 0
	v_mov_b64_e32 v[138:139], 0
	v_mov_b64_e32 v[140:141], 0
	v_mov_b64_e32 v[142:143], 0
	v_mov_b64_e32 v[144:145], 0
	v_mov_b64_e32 v[146:147], 0
	v_mov_b64_e32 v[148:149], 0
	v_mov_b64_e32 v[150:151], 0
	v_mov_b64_e32 v[152:153], 0
	v_mov_b64_e32 v[154:155], 0
	v_mov_b64_e32 v[156:157], 0
	v_mov_b64_e32 v[158:159], 0
	v_mov_b64_e32 v[160:161], 0
